# stack: residual-epilogue gamma in LDS + SSD y-stage x from LDS + first-iteration vmcnt skip after epilogues
# baseline (speedup 1.0000x reference)
; __device__ __forceinline__ unsigned cvt_pk_bf16(float lo, float hi) { unsigned r; asm volatile("v_cvt_pk_bf16_f32 %0, %1, %2" : "=v"(r) : "v"(lo), "v"(hi)); return r; }
;     template <int AI> __device__ __forceinline__ void half_rows(AccT acc, int row0, int col0, int slot, int sq, int fq, const f32x4 (&gsc)[4]) const {
;         v4u xw[4][2];
; #pragma unroll
;         for (int m = 0; m < 4; ++m)
; #pragma unroll
;             for (int bj = 0; bj < 2; ++bj) xw[m][bj] = *(const v4u*)(X + (size_t)(row0 + m * 16) * DM + col0 + bj * HALF);
; #pragma unroll
;         for (int m = 0; m < 4; ++m) { const int row = row0 + m * 16;
;             float ss = 0.f;
; #pragma unroll
;             for (int bj = 0; bj < 2; ++bj) { const size_t off = (size_t)row * DM + col0 + bj * HALF;
;                 float xi[8]; unpack8(xw[m][bj], xi);
;                 const f32x4 x0 = (f32x4){xi[0], xi[1], xi[2], xi[3]} + gsc[bj * 2] * acc[AI][bj][m][0], x1 = (f32x4){xi[4], xi[5], xi[6], xi[7]} + gsc[bj * 2 + 1] * acc[AI][bj][m][1];
;                 { u32x4 xs_; xs_.x = cvt_pk_bf16(x0[0], x0[1]); xs_.y = cvt_pk_bf16(x0[2], x0[3]); xs_.z = cvt_pk_bf16(x1[0], x1[1]); xs_.w = cvt_pk_bf16(x1[2], x1[3]); *(u32x4*)(X + off) = xs_; }
;                 if (NEXT) { ss += ((x0.x * x0.x + x0.y * x0.y) + (x0.z * x0.z + x0.w * x0.w)) + ((x1.x * x1.x + x1.y * x1.y) + (x1.z * x1.z + x1.w * x1.w));
;                     const float* gp_ = gam + (size_t)sq * DM + col0 + bj * HALF; const f32x4 y0 = x0 * *(const f32x4*)gp_, y1 = x1 * *(const f32x4*)(gp_ + 4);
;                     u32x4 w; w.x = cvt_pk_bf16(y0[0], y0[1]); w.y = cvt_pk_bf16(y0[2], y0[3]); w.z = cvt_pk_bf16(y1[0], y1[1]); w.w = cvt_pk_bf16(y1[2], y1[3]);
;                     *(u32x4*)(XB + off) = w; } }
;             if (NEXT) { ss += __shfl_xor(ss, 16); ss += __shfl_xor(ss, 32); if (fq == 0) SSQ[(size_t)row * 16 + slot] = ss; } }
;     }
;     __device__ __forceinline__ void operator()(AccT acc, const Unit& u, int wr, int wc, int fr, int fq) const {
;         const int upm = u.pm, upn = u.pn, uhalf = u.half;
;         const int col0 = upn * BM + wc * 32 + 8 * fq, sq = upm >> 3, slot = upn * 4 + wc, rbase = upm * BM + wr * 64 + fr;
;         f32x4 gsc[4];
; #pragma unroll
;         for (int q = 0; q < 4; ++q) gsc[q] = *(const f32x4*)(gate + (size_t)sq * NMOD + col0 + (q >> 1) * HALF + 4 * (q & 1)) * scale;
.LBB0_557:
	s_mov_b32 s98, 1
	s_ashr_i32 s30, s64, 3
	v_lshl_or_b32 v170, s65, 8, v198
	s_lshl_b32 s34, s65, 2
	v_lshl_add_u32 v184, s64, 8, v1
	s_ashr_i32 s31, s30, 31
	s_mul_i32 s28, s30, 0x9000
	v_ashrrev_i32_e32 v171, 31, v170
	v_ashrrev_i32_e32 v185, 31, v184
	s_mul_hi_i32 s29, s30, 0x9000
	s_add_u32 s28, s14, s28
	v_lshl_add_u64 v[182:183], v[170:171], 1, s[0:1]
	v_lshlrev_b64 v[98:99], 11, v[184:185]
	s_addc_u32 s29, s15, s29
	v_lshlrev_b64 v[172:173], 2, v[170:171]
	v_lshl_add_u64 v[222:223], v[182:183], 0, v[98:99]
	v_lshl_add_u64 v[98:99], s[28:29], 0, v[172:173]
	global_load_dwordx4 v[174:177], v[222:223], off
	global_load_dwordx4 v[178:181], v[98:99], off
	global_load_dwordx4 v[206:209], v[98:99], off offset:16
	s_or_b32 s28, s34, s50
	v_or_b32_e32 v194, 16, v184
	v_or_b32_e32 v190, 32, v184
	v_or_b32_e32 v186, 48, v184
	s_lshl_b64 s[30:31], s[30:31], 12
	s_ashr_i32 s29, s28, 31
	v_ashrrev_i32_e32 v195, 31, v194
	v_ashrrev_i32_e32 v191, 31, v190
	v_ashrrev_i32_e32 v187, 31, v186
	s_add_u32 s30, s16, s30
	v_lshlrev_b64 v[100:101], 11, v[194:195]
	v_lshlrev_b64 v[110:111], 11, v[190:191]
	v_lshlrev_b64 v[112:113], 11, v[186:187]
	global_load_dwordx4 v[210:213], v[222:223], off offset:256
	s_addc_u32 s31, s17, s31
	v_lshl_add_u64 v[196:197], v[182:183], 0, v[100:101]
	v_lshl_add_u64 v[192:193], v[182:183], 0, v[110:111]
	v_lshl_add_u64 v[188:189], v[182:183], 0, v[112:113]
	global_load_dwordx4 v[214:217], v[98:99], off offset:528
	global_load_dwordx4 v[218:221], v[98:99], off offset:512
	global_load_dwordx4 v[150:153], v[196:197], off
	global_load_dwordx4 v[146:149], v[196:197], off offset:256
	global_load_dwordx4 v[134:137], v[192:193], off
	global_load_dwordx4 v[122:125], v[192:193], off offset:256
	global_load_dwordx4 v[110:113], v[188:189], off
	global_load_dwordx4 v[98:101], v[188:189], off offset:256
	v_lshl_add_u64 v[172:173], s[30:31], 0, v[172:173]
	global_load_dwordx4 v[244:247], v[172:173], off
	global_load_dwordx4 v[248:251], v[172:173], off offset:16
	v_lshrrev_b32_e32 v255, 6, v0
	v_lshlrev_b32_e32 v255, 8, v255
	v_bfe_u32 v252, v0, 4, 2
	v_lshl_add_u32 v255, v252, 6, v255
	v_add_u32_e32 v255, 0x20000, v255
	s_waitcnt vmcnt(0)
	ds_write_b128 v255, v[244:247]
	ds_write_b128 v255, v[248:251] offset:16
	global_load_dwordx4 v[244:247], v[172:173], off offset:512
	global_load_dwordx4 v[248:251], v[172:173], off offset:528
	s_waitcnt vmcnt(0)
	ds_write_b128 v255, v[244:247] offset:32
	ds_write_b128 v255, v[248:251] offset:48
	s_waitcnt lgkmcnt(0)
; __device__ __forceinline__ void unpack8(const v4u w, float (&o)[8]) { o[0] = bflo(w.x); o[1] = bfhi(w.x); o[2] = bflo(w.y); o[3] = bfhi(w.y); o[4] = bflo(w.z); o[5] = bfhi(w.z); o[6] = bflo(w.w); o[7] = bfhi(w.w); }
; __device__ __forceinline__ unsigned cvt_pk_bf16(float lo, float hi) { unsigned r; asm volatile("v_cvt_pk_bf16_f32 %0, %1, %2" : "=v"(r) : "v"(lo), "v"(hi)); return r; }
;     template <int AI> __device__ __forceinline__ void half_rows(AccT acc, int row0, int col0, int slot, int sq, int fq, const f32x4 (&gsc)[4]) const {
;     ...
;         for (int m = 0; m < 4; ++m) { const int row = row0 + m * 16;
;             float ss = 0.f;
; #pragma unroll
;             for (int bj = 0; bj < 2; ++bj) { const size_t off = (size_t)row * DM + col0 + bj * HALF;
;                 float xi[8]; unpack8(xw[m][bj], xi);
;                 const f32x4 x0 = (f32x4){xi[0], xi[1], xi[2], xi[3]} + gsc[bj * 2] * acc[AI][bj][m][0], x1 = (f32x4){xi[4], xi[5], xi[6], xi[7]} + gsc[bj * 2 + 1] * acc[AI][bj][m][1];
;                 { u32x4 xs_; xs_.x = cvt_pk_bf16(x0[0], x0[1]); xs_.y = cvt_pk_bf16(x0[2], x0[3]); xs_.z = cvt_pk_bf16(x1[0], x1[1]); xs_.w = cvt_pk_bf16(x1[2], x1[3]); *(u32x4*)(X + off) = xs_; }
;                 if (NEXT) { ss += ((x0.x * x0.x + x0.y * x0.y) + (x0.z * x0.z + x0.w * x0.w)) + ((x1.x * x1.x + x1.y * x1.y) + (x1.z * x1.z + x1.w * x1.w));
;                     const float* gp_ = gam + (size_t)sq * DM + col0 + bj * HALF; const f32x4 y0 = x0 * *(const f32x4*)gp_, y1 = x1 * *(const f32x4*)(gp_ + 4);
;                     u32x4 w; w.x = cvt_pk_bf16(y0[0], y0[1]); w.y = cvt_pk_bf16(y0[2], y0[3]); w.z = cvt_pk_bf16(y1[0], y1[1]); w.w = cvt_pk_bf16(y1[2], y1[3]);
;                     *(u32x4*)(XB + off) = w; } }
;             if (NEXT) { ss += __shfl_xor(ss, 16); ss += __shfl_xor(ss, 32); if (fq == 0) SSQ[(size_t)row * 16 + slot] = ss; } }
	v_lshlrev_b32_e32 v224, 16, v174
	v_and_b32_e32 v225, 0xffff0000, v174
	v_lshlrev_b32_e32 v226, 16, v175
	v_and_b32_e32 v227, 0xffff0000, v175
	v_lshlrev_b32_e32 v228, 16, v176
	v_and_b32_e32 v229, 0xffff0000, v176
	v_lshlrev_b32_e32 v230, 16, v177
	v_and_b32_e32 v231, 0xffff0000, v177
	v_pk_mul_f32 v[180:181], v[180:181], 0.5 op_sel_hi:[1,0]
	v_pk_mul_f32 v[178:179], v[178:179], 0.5 op_sel_hi:[1,0]
	v_pk_mul_f32 v[176:177], v[208:209], 0.5 op_sel_hi:[1,0]
	v_pk_mul_f32 v[174:175], v[206:207], 0.5 op_sel_hi:[1,0]
	v_pk_fma_f32 v[226:227], v[144:145], v[180:181], v[226:227]
	v_pk_fma_f32 v[232:233], v[142:143], v[178:179], v[224:225]
	v_pk_fma_f32 v[230:231], v[140:141], v[176:177], v[230:231]
	v_pk_fma_f32 v[228:229], v[138:139], v[174:175], v[228:229]
	v_cvt_pk_bf16_f32 v138, v232, v233
	v_cvt_pk_bf16_f32 v139, v226, v227
	v_lshlrev_b32_e32 v242, 16, v212
	v_cvt_pk_bf16_f32 v140, v228, v229
	v_cvt_pk_bf16_f32 v141, v230, v231
	global_store_dwordx4 v[222:223], v[138:141], off
	ds_read_b128 v[206:209], v255
	s_nop 0
	ds_read_b128 v[222:225], v255 offset:16
	v_lshlrev_b64 v[138:139], 10, v[184:185]
	v_lshl_add_u64 v[138:139], v[138:139], 0, v[170:171]
	v_lshlrev_b64 v[234:235], 1, v[138:139]
	v_and_b32_e32 v243, 0xffff0000, v212
	v_lshlrev_b32_e32 v212, 16, v213
	v_and_b32_e32 v213, 0xffff0000, v213
	v_pk_mul_f32 v[140:141], v[216:217], 0.5 op_sel_hi:[1,0]
	v_pk_mul_f32 v[138:139], v[214:215], 0.5 op_sel_hi:[1,0]
	v_lshl_add_u64 v[236:237], s[10:11], 0, v[234:235]
	v_or_b32_e32 v234, 0x100, v234
	v_lshlrev_b32_e32 v240, 16, v210
	v_and_b32_e32 v241, 0xffff0000, v210
	v_lshlrev_b32_e32 v210, 16, v211
	v_and_b32_e32 v211, 0xffff0000, v211
	v_pk_mul_f32 v[144:145], v[220:221], 0.5 op_sel_hi:[1,0]
	v_pk_mul_f32 v[142:143], v[218:219], 0.5 op_sel_hi:[1,0]
	v_pk_fma_f32 v[212:213], v[128:129], v[140:141], v[212:213]
	v_pk_fma_f32 v[216:217], v[126:127], v[138:139], v[242:243]
	v_lshl_add_u64 v[238:239], s[0:1], 0, v[234:235]
	v_pk_fma_f32 v[210:211], v[132:133], v[144:145], v[210:211]
	v_pk_fma_f32 v[214:215], v[130:131], v[142:143], v[240:241]
	v_mul_f32_e32 v205, v229, v229
	v_mul_f32_e32 v218, v231, v231
	v_mul_f32_e32 v219, v215, v215
	v_mul_f32_e32 v220, v211, v211
	v_mul_f32_e32 v221, v217, v217
	v_fmac_f32_e32 v205, v228, v228
	v_fmac_f32_e32 v218, v230, v230
	v_fmac_f32_e32 v219, v214, v214
	v_fmac_f32_e32 v220, v210, v210
	v_fmac_f32_e32 v221, v216, v216
	s_waitcnt lgkmcnt(0)
	v_pk_mul_f32 v[128:129], v[226:227], v[208:209]
	v_pk_mul_f32 v[126:127], v[232:233], v[206:207]
	s_waitcnt lgkmcnt(0)
	v_pk_mul_f32 v[130:131], v[230:231], v[224:225]
	v_pk_mul_f32 v[132:133], v[228:229], v[222:223]
	v_cvt_pk_bf16_f32 v126, v126, v127
	v_cvt_pk_bf16_f32 v127, v128, v129
	v_mul_f32_e32 v222, v213, v213
	v_cvt_pk_bf16_f32 v128, v132, v133
	v_cvt_pk_bf16_f32 v129, v130, v131
	global_store_dwordx4 v[236:237], v[126:129], off
	v_fmac_f32_e32 v222, v212, v212
	s_nop 0
	v_cvt_pk_bf16_f32 v126, v214, v215
	v_cvt_pk_bf16_f32 v127, v210, v211
	v_cvt_pk_bf16_f32 v128, v216, v217
	v_cvt_pk_bf16_f32 v129, v212, v213
	global_store_dwordx4 v[238:239], v[126:129], off
	ds_read_b128 v[130:133], v255 offset:32
	ds_read_b128 v[206:209], v255 offset:48
	v_and_b32_e32 v127, 64, v204
	v_mul_f32_e32 v128, v233, v233
	v_mul_f32_e32 v129, v227, v227
	v_xor_b32_e32 v126, 16, v204
	v_add_u32_e32 v127, 64, v127
	v_fmac_f32_e32 v128, v232, v232
	v_fmac_f32_e32 v129, v226, v226
	v_cmp_lt_i32_e32 vcc, v126, v127
	v_add_f32_e32 v128, v128, v129
	v_add_f32_e32 v129, v205, v218
	v_add_f32_e32 v205, v219, v220
	v_add_f32_e32 v218, v221, v222
	v_cndmask_b32_e32 v126, v204, v126, vcc
	v_add_f32_e32 v128, v128, v129
	v_add_f32_e32 v129, v205, v218
	v_lshlrev_b32_e32 v126, 2, v126
	v_add_f32_e32 v128, v128, v129
	ds_bpermute_b32 v129, v126, v128
	v_xor_b32_e32 v205, 32, v204
	v_cmp_lt_i32_e32 vcc, v205, v127
	s_waitcnt lgkmcnt(0)
	v_add_f32_e32 v128, v128, v129
	v_cndmask_b32_e32 v127, v204, v205, vcc
	v_lshlrev_b32_e32 v127, 2, v127
	ds_bpermute_b32 v129, v127, v128
	s_waitcnt lgkmcnt(0)
	v_pk_mul_f32 v[132:133], v[210:211], v[132:133]
	v_pk_mul_f32 v[130:131], v[214:215], v[130:131]
	s_waitcnt lgkmcnt(0)
	v_pk_mul_f32 v[206:207], v[216:217], v[206:207]
	v_cvt_pk_bf16_f32 v130, v130, v131
	v_cvt_pk_bf16_f32 v131, v132, v133
	v_pk_mul_f32 v[208:209], v[212:213], v[208:209]
	v_cvt_pk_bf16_f32 v132, v206, v207
	v_lshl_add_u64 v[206:207], s[10:11], 0, v[234:235]
	v_cvt_pk_bf16_f32 v133, v208, v209
	global_store_dwordx4 v[206:207], v[130:133], off
	s_and_saveexec_b64 s[30:31], s[4:5]
	s_cbranch_execz .LBB0_559
	v_lshlrev_b64 v[130:131], 6, v[184:185]
	v_lshl_add_u64 v[130:131], s[12:13], 0, v[130:131]
	v_lshl_add_u64 v[130:131], s[28:29], 2, v[130:131]
	s_waitcnt lgkmcnt(0)
	v_add_f32_e32 v128, v128, v129
	global_store_dword v[130:131], v128, off

; __device__ __forceinline__ unsigned cvt_pk_bf16(float lo, float hi) { unsigned r; asm volatile("v_cvt_pk_bf16_f32 %0, %1, %2" : "=v"(r) : "v"(lo), "v"(hi)); return r; }
;     template <int AI> __device__ __forceinline__ void half_rows(AccT acc, int row0, int col0, int slot, int sq, int fq, const f32x4 (&gsc)[4]) const {
;         v4u xw[4][2];
; #pragma unroll
;         for (int m = 0; m < 4; ++m)
; #pragma unroll
;             for (int bj = 0; bj < 2; ++bj) xw[m][bj] = *(const v4u*)(X + (size_t)(row0 + m * 16) * DM + col0 + bj * HALF);
; #pragma unroll
;         for (int m = 0; m < 4; ++m) { const int row = row0 + m * 16;
;             float ss = 0.f;
; #pragma unroll
;             for (int bj = 0; bj < 2; ++bj) { const size_t off = (size_t)row * DM + col0 + bj * HALF;
;                 float xi[8]; unpack8(xw[m][bj], xi);
;                 const f32x4 x0 = (f32x4){xi[0], xi[1], xi[2], xi[3]} + gsc[bj * 2] * acc[AI][bj][m][0], x1 = (f32x4){xi[4], xi[5], xi[6], xi[7]} + gsc[bj * 2 + 1] * acc[AI][bj][m][1];
;                 { u32x4 xs_; xs_.x = cvt_pk_bf16(x0[0], x0[1]); xs_.y = cvt_pk_bf16(x0[2], x0[3]); xs_.z = cvt_pk_bf16(x1[0], x1[1]); xs_.w = cvt_pk_bf16(x1[2], x1[3]); *(u32x4*)(X + off) = xs_; }
;                 if (NEXT) { ss += ((x0.x * x0.x + x0.y * x0.y) + (x0.z * x0.z + x0.w * x0.w)) + ((x1.x * x1.x + x1.y * x1.y) + (x1.z * x1.z + x1.w * x1.w));
;                     const float* gp_ = gam + (size_t)sq * DM + col0 + bj * HALF; const f32x4 y0 = x0 * *(const f32x4*)gp_, y1 = x1 * *(const f32x4*)(gp_ + 4);
;                     u32x4 w; w.x = cvt_pk_bf16(y0[0], y0[1]); w.y = cvt_pk_bf16(y0[2], y0[3]); w.z = cvt_pk_bf16(y1[0], y1[1]); w.w = cvt_pk_bf16(y1[2], y1[3]);
;                     *(u32x4*)(XB + off) = w; } }
;             if (NEXT) { ss += __shfl_xor(ss, 16); ss += __shfl_xor(ss, 32); if (fq == 0) SSQ[(size_t)row * 16 + slot] = ss; } }
;     }
;     __device__ __forceinline__ void operator()(AccT acc, const Unit& u, int wr, int wc, int fr, int fq) const {
;         const int upm = u.pm, upn = u.pn, uhalf = u.half;
;         const int col0 = upn * BM + wc * 32 + 8 * fq, sq = upm >> 3, slot = upn * 4 + wc, rbase = upm * BM + wr * 64 + fr;
;         f32x4 gsc[4];
; #pragma unroll
;         for (int q = 0; q < 4; ++q) gsc[q] = *(const f32x4*)(gate + (size_t)sq * NMOD + col0 + (q >> 1) * HALF + 4 * (q & 1)) * scale;
.LBB0_2136:
	s_mov_b32 s98, 1
	v_lshl_or_b32 v186, s36, 8, v206
	s_ashr_i32 s38, s34, 3
	v_lshl_add_u32 v192, s34, 8, v1
	s_lshl_b32 s25, s36, 2
	v_ashrrev_i32_e32 v187, 31, v186
	v_ashrrev_i32_e32 v193, 31, v192
	s_ashr_i32 s39, s38, 31
	s_mul_i32 s34, s38, 0x9000
	v_lshl_add_u64 v[190:191], v[186:187], 1, s[0:1]
	v_lshlrev_b64 v[34:35], 11, v[192:193]
	s_mul_hi_i32 s27, s38, 0x9000
	s_add_u32 s34, s12, s34
	v_lshl_add_u64 v[222:223], v[190:191], 0, v[34:35]
	s_addc_u32 s35, s13, s27
	v_lshlrev_b64 v[188:189], 2, v[186:187]
	global_load_dwordx4 v[214:217], v[222:223], off
	v_lshl_add_u64 v[38:39], s[34:35], 0, v[188:189]
	global_load_dwordx4 v[46:49], v[38:39], off
	global_load_dwordx4 v[42:45], v[38:39], off offset:16
	s_or_b32 s34, s25, s56
	v_or_b32_e32 v202, 16, v192
	v_or_b32_e32 v198, 32, v192
	v_or_b32_e32 v194, 48, v192
	s_lshl_b64 s[36:37], s[38:39], 12
	s_ashr_i32 s35, s34, 31
	v_ashrrev_i32_e32 v203, 31, v202
	v_ashrrev_i32_e32 v199, 31, v198
	v_ashrrev_i32_e32 v195, 31, v194
	s_add_u32 s36, s14, s36
	v_lshlrev_b64 v[34:35], 11, v[202:203]
	v_lshlrev_b64 v[36:37], 11, v[198:199]
	v_lshlrev_b64 v[40:41], 11, v[194:195]
	global_load_dwordx4 v[218:221], v[222:223], off offset:256
	s_addc_u32 s37, s15, s37
	v_lshl_add_u64 v[204:205], v[190:191], 0, v[34:35]
	v_lshl_add_u64 v[200:201], v[190:191], 0, v[36:37]
	v_lshl_add_u64 v[196:197], v[190:191], 0, v[40:41]
	global_load_dwordx4 v[34:37], v[38:39], off offset:528
	s_nop 0
	global_load_dwordx4 v[38:41], v[38:39], off offset:512
	s_nop 0
	global_load_dwordx4 v[166:169], v[204:205], off
	global_load_dwordx4 v[162:165], v[204:205], off offset:256
	global_load_dwordx4 v[150:153], v[200:201], off
	global_load_dwordx4 v[138:141], v[200:201], off offset:256
	global_load_dwordx4 v[126:129], v[196:197], off
	global_load_dwordx4 v[114:117], v[196:197], off offset:256
	v_lshl_add_u64 v[188:189], s[36:37], 0, v[188:189]
	global_load_dwordx4 v[244:247], v[188:189], off
	global_load_dwordx4 v[248:251], v[188:189], off offset:16
	v_lshrrev_b32_e32 v255, 6, v0
	v_lshlrev_b32_e32 v255, 8, v255
	v_bfe_u32 v252, v0, 4, 2
	v_lshl_add_u32 v255, v252, 6, v255
	v_add_u32_e32 v255, 0x20000, v255
	s_waitcnt vmcnt(0)
	ds_write_b128 v255, v[244:247]
	ds_write_b128 v255, v[248:251] offset:16
	global_load_dwordx4 v[244:247], v[188:189], off offset:512
	global_load_dwordx4 v[248:251], v[188:189], off offset:528
	s_waitcnt vmcnt(0)
	ds_write_b128 v255, v[244:247] offset:32
	ds_write_b128 v255, v[248:251] offset:48
	s_waitcnt lgkmcnt(0)
	v_lshlrev_b32_e32 v224, 16, v214
	v_and_b32_e32 v225, 0xffff0000, v214
	v_lshlrev_b32_e32 v214, 16, v215
	v_and_b32_e32 v215, 0xffff0000, v215
	v_lshlrev_b32_e32 v226, 16, v216
	v_and_b32_e32 v227, 0xffff0000, v216
	v_lshlrev_b32_e32 v216, 16, v217
	v_and_b32_e32 v217, 0xffff0000, v217
	v_pk_fma_f32 v[214:215], v[160:161], v[48:49], v[214:215]
	v_pk_fma_f32 v[224:225], v[158:159], v[46:47], v[224:225]
	v_pk_fma_f32 v[216:217], v[156:157], v[44:45], v[216:217]
	v_pk_fma_f32 v[226:227], v[154:155], v[42:43], v[226:227]
	v_cvt_pk_bf16_f32 v154, v224, v225
	v_cvt_pk_bf16_f32 v155, v214, v215
	v_lshlrev_b32_e32 v234, 16, v220
	v_cvt_pk_bf16_f32 v156, v226, v227
	v_cvt_pk_bf16_f32 v157, v216, v217
	global_store_dwordx4 v[222:223], v[154:157], off
	ds_read_b128 v[154:157], v255
	s_nop 0
	ds_read_b128 v[158:161], v255 offset:16
	v_lshlrev_b64 v[222:223], 10, v[192:193]
	v_lshl_add_u64 v[222:223], v[222:223], 0, v[186:187]
	v_lshlrev_b64 v[222:223], 1, v[222:223]
	v_and_b32_e32 v235, 0xffff0000, v220
	v_lshlrev_b32_e32 v220, 16, v221
	v_and_b32_e32 v221, 0xffff0000, v221
	v_lshl_add_u64 v[228:229], s[8:9], 0, v[222:223]
	v_or_b32_e32 v222, 0x100, v222
	v_lshlrev_b32_e32 v232, 16, v218
	v_and_b32_e32 v233, 0xffff0000, v218
	v_lshlrev_b32_e32 v218, 16, v219
	v_and_b32_e32 v219, 0xffff0000, v219
	v_pk_fma_f32 v[220:221], v[144:145], v[36:37], v[220:221]
	v_pk_fma_f32 v[234:235], v[142:143], v[34:35], v[234:235]
	v_lshl_add_u64 v[230:231], s[0:1], 0, v[222:223]
	v_pk_fma_f32 v[218:219], v[148:149], v[40:41], v[218:219]
	v_pk_fma_f32 v[232:233], v[146:147], v[38:39], v[232:233]
	v_mul_f32_e32 v213, v235, v235
	v_fmac_f32_e32 v213, v234, v234
	s_waitcnt lgkmcnt(0)
	v_pk_mul_f32 v[144:145], v[214:215], v[156:157]
	v_pk_mul_f32 v[142:143], v[224:225], v[154:155]
	s_waitcnt lgkmcnt(0)
	v_pk_mul_f32 v[146:147], v[216:217], v[160:161]
	v_pk_mul_f32 v[148:149], v[226:227], v[158:159]
	v_cvt_pk_bf16_f32 v142, v142, v143
	v_cvt_pk_bf16_f32 v143, v144, v145
	v_mul_f32_e32 v158, v227, v227
	v_cvt_pk_bf16_f32 v144, v148, v149
	v_cvt_pk_bf16_f32 v145, v146, v147
	global_store_dwordx4 v[228:229], v[142:145], off
	v_mul_f32_e32 v159, v217, v217
	v_mul_f32_e32 v160, v233, v233
	v_cvt_pk_bf16_f32 v142, v232, v233
	v_cvt_pk_bf16_f32 v143, v218, v219
	v_cvt_pk_bf16_f32 v144, v234, v235
	v_cvt_pk_bf16_f32 v145, v220, v221
	global_store_dwordx4 v[230:231], v[142:145], off
	ds_read_b128 v[146:149], v255 offset:32
	ds_read_b128 v[154:157], v255 offset:48
	v_and_b32_e32 v143, 64, v212
	v_mul_f32_e32 v144, v225, v225
	v_mul_f32_e32 v145, v215, v215
	v_mul_f32_e32 v161, v219, v219
	v_mul_f32_e32 v215, v221, v221
	v_xor_b32_e32 v142, 16, v212
	v_add_u32_e32 v143, 64, v143
	v_fmac_f32_e32 v144, v224, v224
	v_fmac_f32_e32 v145, v214, v214
	v_fmac_f32_e32 v158, v226, v226
	v_fmac_f32_e32 v159, v216, v216
	v_fmac_f32_e32 v160, v232, v232
	v_fmac_f32_e32 v161, v218, v218
	v_fmac_f32_e32 v215, v220, v220
	v_cmp_lt_i32_e32 vcc, v142, v143
	v_add_f32_e32 v144, v144, v145
	v_add_f32_e32 v145, v158, v159
	v_add_f32_e32 v158, v160, v161
	v_add_f32_e32 v159, v213, v215
	v_cndmask_b32_e32 v142, v212, v142, vcc
	v_add_f32_e32 v144, v144, v145
	v_add_f32_e32 v145, v158, v159
	v_lshlrev_b32_e32 v142, 2, v142
	v_add_f32_e32 v144, v144, v145
	ds_bpermute_b32 v145, v142, v144
	v_xor_b32_e32 v158, 32, v212
	v_cmp_lt_i32_e32 vcc, v158, v143
	s_waitcnt lgkmcnt(0)
	v_add_f32_e32 v144, v144, v145
	v_cndmask_b32_e32 v143, v212, v158, vcc
	v_lshlrev_b32_e32 v143, 2, v143
	ds_bpermute_b32 v145, v143, v144
	s_waitcnt lgkmcnt(0)
	v_pk_mul_f32 v[148:149], v[218:219], v[148:149]
	v_pk_mul_f32 v[146:147], v[232:233], v[146:147]
	s_waitcnt lgkmcnt(0)
	v_pk_mul_f32 v[154:155], v[234:235], v[154:155]
	v_cvt_pk_bf16_f32 v146, v146, v147
	v_cvt_pk_bf16_f32 v147, v148, v149
	v_pk_mul_f32 v[156:157], v[220:221], v[156:157]
	v_cvt_pk_bf16_f32 v148, v154, v155
	v_lshl_add_u64 v[154:155], s[8:9], 0, v[222:223]
	v_cvt_pk_bf16_f32 v149, v156, v157
	global_store_dwordx4 v[154:155], v[146:149], off
	s_and_saveexec_b64 s[36:37], s[4:5]
	s_cbranch_execz .LBB0_2138
	v_lshlrev_b64 v[146:147], 6, v[192:193]
	v_lshl_add_u64 v[146:147], s[10:11], 0, v[146:147]
	v_lshl_add_u64 v[146:147], s[34:35], 2, v[146:147]
	s_waitcnt lgkmcnt(0)
	v_add_f32_e32 v144, v144, v145
	global_store_dword v[146:147], v144, off
